# best2 + W8 staging in one round trip + DPP wave reductions in the rmsnorm rows loop
# speedup vs baseline: 1.0242x; 1.0078x over previous
.Lpost_getpc1:
	s_add_u32 s98, s98, (.LBB0_930-.Lpost_getpc1)&4294967295
	s_addc_u32 s99, s99, (.LBB0_930-.Lpost_getpc1)>>32
	s_setpc_b64 s[98:99]
	s_nop 0
	s_nop 0
	s_nop 0
	s_nop 0
	s_nop 0
	s_nop 0
	s_nop 0
	s_nop 0
	s_nop 0
	s_nop 0
	s_nop 0
	s_nop 0
	s_nop 0
	s_nop 0
	s_nop 0
	s_nop 0
	s_nop 0
	s_nop 0
	s_nop 0
	s_nop 0
	s_nop 0
	s_nop 0
	s_nop 0
	s_nop 0
	s_nop 0
	s_nop 0
	s_nop 0
	s_nop 0
	s_nop 0
	s_nop 0
	s_nop 0
	s_nop 0
	s_nop 0
	s_nop 0
	s_nop 0
	s_nop 0
	s_nop 0
	s_nop 0
	s_nop 0
	s_nop 0
	s_nop 0
	s_nop 0
	s_nop 0
	s_nop 0
	s_nop 0
	s_nop 0
	s_nop 0
	s_nop 0
	s_nop 0
	s_nop 0
	s_nop 0
	s_nop 0
	s_nop 0
	s_nop 0
	s_nop 0
	s_nop 0
	s_nop 0
	s_nop 0
	s_nop 0
	s_nop 0
	s_nop 0
	s_nop 0
